# attention row-max: the redundant canonicalising v_max pairs around the lane-half exchange removed (4 VALU ops fewer per key tile per wave), on top of the saddr K-loop version
# speedup vs baseline: 1.0020x; 1.0009x over previous
.LBB0_498:
	v_add_u32_e32 v208, s6, v220
	ds_read_b64_tr_b16 v[194:195], v208 offset:24576
	ds_read_b64_tr_b16 v[196:197], v208 offset:25088
	s_waitcnt lgkmcnt(9)
	v_mfma_f32_32x32x16_bf16 v[114:129], v[190:193], v[150:153], v[50:65]
	v_add_f32_e32 v98, v82, v83
	v_add_f32_e32 v98, v84, v98
	v_add_f32_e32 v98, v85, v98
	v_add_f32_e32 v98, v86, v98
	v_add_f32_e32 v98, v87, v98
	v_cvt_pk_bf16_f32 v158, v82, v83
	v_cvt_pk_bf16_f32 v159, v84, v85
	ds_read_b64_tr_b16 v[190:191], v208 offset:28672
	ds_read_b64_tr_b16 v[192:193], v208 offset:29184
	v_add_f32_e32 v82, v88, v98
	s_waitcnt lgkmcnt(10)
	v_mfma_f32_32x32x16_bf16 v[98:113], v[186:189], v[150:153], v[50:65]
	v_add_f32_e32 v82, v89, v82
	v_add_f32_e32 v82, v90, v82
	v_add_f32_e32 v82, v91, v82
	v_cvt_pk_bf16_f32 v160, v86, v87
	v_cvt_pk_bf16_f32 v161, v88, v89
	ds_read_b64_tr_b16 v[186:187], v208 offset:25600
	ds_read_b64_tr_b16 v[188:189], v208 offset:26112
	s_waitcnt lgkmcnt(11)
	v_mfma_f32_32x32x16_bf16 v[114:129], v[182:185], v[142:145], v[114:129]
	v_add_f32_e32 v82, v92, v82
	v_add_f32_e32 v82, v93, v82
	v_add_f32_e32 v82, v94, v82
	v_add_f32_e32 v82, v95, v82
	v_cvt_pk_bf16_f32 v154, v90, v91
	v_cvt_pk_bf16_f32 v155, v92, v93
	ds_read_b64_tr_b16 v[90:91], v208 offset:29696
	ds_read_b64_tr_b16 v[92:93], v208 offset:30208
	s_waitcnt lgkmcnt(12)
	v_mfma_f32_32x32x16_bf16 v[98:113], v[178:181], v[142:145], v[98:113]
	v_add_f32_e32 v82, v96, v82
	v_add_f32_e32 v82, v97, v82
	v_add_f32_e32 v82, v66, v82
	v_add_f32_e32 v82, v67, v82
	v_cvt_pk_bf16_f32 v156, v94, v95
	v_cvt_pk_bf16_f32 v157, v96, v97
	ds_read_b64_tr_b16 v[86:87], v208 offset:26624
	ds_read_b64_tr_b16 v[88:89], v208 offset:27136
	s_waitcnt lgkmcnt(13)
	v_mfma_f32_32x32x16_bf16 v[114:129], v[174:177], v[134:137], v[114:129]
	v_add_f32_e32 v82, v68, v82
	v_add_f32_e32 v82, v69, v82
	v_add_f32_e32 v82, v70, v82
	v_add_f32_e32 v94, v71, v82
	v_cvt_pk_bf16_f32 v146, v66, v67
	v_cvt_pk_bf16_f32 v147, v68, v69
	ds_read_b64_tr_b16 v[82:83], v208 offset:30720
	ds_read_b64_tr_b16 v[84:85], v208 offset:31232
	s_waitcnt lgkmcnt(14)
	v_mfma_f32_32x32x16_bf16 v[98:113], v[170:173], v[134:137], v[98:113]
	v_add_f32_e32 v66, v72, v94
	v_add_f32_e32 v66, v73, v66
	v_add_f32_e32 v66, v74, v66
	v_add_f32_e32 v66, v75, v66
	v_cvt_pk_bf16_f32 v148, v70, v71
	v_cvt_pk_bf16_f32 v149, v72, v73
	ds_read_b64_tr_b16 v[70:71], v208 offset:27648
	ds_read_b64_tr_b16 v[72:73], v208 offset:28160
	s_waitcnt lgkmcnt(14)
	v_mfma_f32_32x32x16_bf16 v[114:129], v[166:169], v[130:133], v[114:129]
	v_add_f32_e32 v66, v76, v66
	v_add_f32_e32 v66, v77, v66
	v_add_f32_e32 v66, v78, v66
	v_add_f32_e32 v94, v79, v66
	v_cvt_pk_bf16_f32 v138, v74, v75
	v_cvt_pk_bf16_f32 v139, v76, v77
	ds_read_b64_tr_b16 v[66:67], v208 offset:31744
	ds_read_b64_tr_b16 v[68:69], v208 offset:32256
	v_mfma_f32_32x32x16_bf16 v[98:113], v[162:165], v[130:133], v[98:113]
	v_add_f32_e32 v74, v80, v94
	v_add_f32_e32 v74, v81, v74
	v_add_f32_e32 v76, 0, v74
	v_cvt_pk_bf16_f32 v140, v78, v79
	v_cvt_pk_bf16_f32 v141, v80, v81
	v_lshl_add_u64 v[74:75], v[204:205], 0, s[68:69]
	s_add_i32 s3, s12, s49
	s_mov_b32 s6, m0
	s_mov_b32 m0, s3
	s_nop 0
	global_load_lds_dwordx4 v[74:75], off
	s_mov_b32 m0, s6
	v_lshl_add_u64 v[74:75], v[202:203], 0, s[68:69]
	s_add_i32 s3, s63, s61
	s_mov_b32 s6, m0
	s_mov_b32 m0, s3
	s_nop 0
	global_load_lds_dwordx4 v[74:75], off
	s_mov_b32 m0, s6
	s_nop 0
	s_nop 0
	v_max_f32_e32 v74, v114, v115
	v_max3_f32 v75, v116, v117, v99
	v_max3_f32 v74, v74, v98, v100
	v_max3_f32 v74, v74, v101, v118
	v_max3_f32 v75, v75, v120, v121
	v_max3_f32 v74, v74, v119, v102
	v_max3_f32 v75, v75, v104, v105
	v_max3_f32 v74, v74, v103, v122
	v_max3_f32 v75, v75, v124, v125
	v_max3_f32 v74, v74, v123, v106
	v_max3_f32 v75, v75, v108, v109
	v_max3_f32 v74, v74, v107, v126
	v_max3_f32 v75, v75, v128, v129
	v_max3_f32 v74, v74, v127, v110
	v_max3_f32 v75, v75, v112, v113
	v_max3_f32 v74, v74, v111, v75
	v_mov_b32_e32 v75, v74
	s_nop 1
	v_permlane32_swap_b32_e32 v74, v75
	s_nop 0
	s_nop 0
	v_max_f32_e32 v74, v74, v75
	v_cmp_lt_f32_e32 vcc, s33, v74
	s_cmp_lg_u64 vcc, 0
	v_add_f32_e32 v208, v222, v76
	s_cselect_b64 s[6:7], -1, 0
	s_cbranch_vccnz .LBB0_506

.LBB0_501:
	s_add_i32 s3, s63, 0x2000
	s_cmpk_lg_i32 s63, 0x4000
	s_cselect_b32 s62, s3, 0
	v_add_u32_e32 v210, s12, v220
	ds_read_b64_tr_b16 v[170:171], v210 offset:24576
	ds_read_b64_tr_b16 v[172:173], v210 offset:25088
	s_waitcnt lgkmcnt(9)
	v_mfma_f32_32x32x16_bf16 v[82:97], v[74:77], v[150:153], v[50:65]
	v_add_f32_e32 v66, v114, v115
	v_add_f32_e32 v66, v116, v66
	v_add_f32_e32 v66, v117, v66
	v_add_f32_e32 v66, v118, v66
	v_add_f32_e32 v66, v119, v66
	v_cvt_pk_bf16_f32 v158, v114, v115
	v_cvt_pk_bf16_f32 v159, v116, v117
	ds_read_b64_tr_b16 v[166:167], v210 offset:28672
	ds_read_b64_tr_b16 v[168:169], v210 offset:29184
	v_add_f32_e32 v66, v120, v66
	v_add_f32_e32 v66, v121, v66
	v_add_f32_e32 v66, v122, v66
	v_add_f32_e32 v114, v123, v66
	s_waitcnt lgkmcnt(10)
	v_mfma_f32_32x32x16_bf16 v[66:81], v[162:165], v[150:153], v[50:65]
	v_cvt_pk_bf16_f32 v160, v118, v119
	v_cvt_pk_bf16_f32 v161, v120, v121
	ds_read_b64_tr_b16 v[162:163], v210 offset:25600
	ds_read_b64_tr_b16 v[164:165], v210 offset:26112
	s_waitcnt lgkmcnt(11)
	v_mfma_f32_32x32x16_bf16 v[82:97], v[194:197], v[142:145], v[82:97]
	v_add_f32_e32 v114, v124, v114
	v_add_f32_e32 v114, v125, v114
	v_add_f32_e32 v114, v126, v114
	v_add_f32_e32 v114, v127, v114
	v_cvt_pk_bf16_f32 v154, v122, v123
	v_cvt_pk_bf16_f32 v155, v124, v125
	ds_read_b64_tr_b16 v[122:123], v210 offset:29696
	ds_read_b64_tr_b16 v[124:125], v210 offset:30208
	s_waitcnt lgkmcnt(12)
	v_mfma_f32_32x32x16_bf16 v[66:81], v[186:189], v[142:145], v[66:81]
	v_add_f32_e32 v114, v128, v114
	v_add_f32_e32 v114, v129, v114
	v_add_f32_e32 v114, v98, v114
	v_add_f32_e32 v114, v99, v114
	v_cvt_pk_bf16_f32 v156, v126, v127
	v_cvt_pk_bf16_f32 v157, v128, v129
	ds_read_b64_tr_b16 v[118:119], v210 offset:26624
	ds_read_b64_tr_b16 v[120:121], v210 offset:27136
	s_waitcnt lgkmcnt(13)
	v_mfma_f32_32x32x16_bf16 v[82:97], v[190:193], v[134:137], v[82:97]
	v_add_f32_e32 v114, v100, v114
	v_add_f32_e32 v114, v101, v114
	v_add_f32_e32 v114, v102, v114
	v_add_f32_e32 v126, v103, v114
	v_cvt_pk_bf16_f32 v146, v98, v99
	v_cvt_pk_bf16_f32 v147, v100, v101
	ds_read_b64_tr_b16 v[114:115], v210 offset:30720
	ds_read_b64_tr_b16 v[116:117], v210 offset:31232
	s_waitcnt lgkmcnt(14)
	v_mfma_f32_32x32x16_bf16 v[66:81], v[178:181], v[134:137], v[66:81]
	v_add_f32_e32 v98, v104, v126
	v_add_f32_e32 v98, v105, v98
	v_add_f32_e32 v98, v106, v98
	v_add_f32_e32 v98, v107, v98
	v_cvt_pk_bf16_f32 v148, v102, v103
	v_cvt_pk_bf16_f32 v149, v104, v105
	ds_read_b64_tr_b16 v[102:103], v210 offset:27648
	ds_read_b64_tr_b16 v[104:105], v210 offset:28160
	s_waitcnt lgkmcnt(14)
	v_mfma_f32_32x32x16_bf16 v[82:97], v[182:185], v[130:133], v[82:97]
	v_add_f32_e32 v98, v108, v98
	v_add_f32_e32 v98, v109, v98
	v_add_f32_e32 v98, v110, v98
	v_add_f32_e32 v126, v111, v98
	v_cvt_pk_bf16_f32 v138, v106, v107
	v_cvt_pk_bf16_f32 v139, v108, v109
	ds_read_b64_tr_b16 v[98:99], v210 offset:31744
	ds_read_b64_tr_b16 v[100:101], v210 offset:32256
	v_mfma_f32_32x32x16_bf16 v[66:81], v[174:177], v[130:133], v[66:81]
	v_add_f32_e32 v106, v112, v126
	v_add_f32_e32 v106, v113, v106
	v_add_f32_e32 v106, 0, v106
	v_cvt_pk_bf16_f32 v140, v110, v111
	v_cvt_pk_bf16_f32 v141, v112, v113
	s_nop 0
	s_nop 0
	v_max_f32_e32 v107, v82, v83
	s_nop 3
	v_max3_f32 v108, v84, v85, v67
	v_max3_f32 v107, v107, v66, v68
	v_max3_f32 v107, v107, v69, v86
	v_max3_f32 v108, v108, v88, v89
	v_max3_f32 v107, v107, v87, v70
	v_max3_f32 v108, v108, v72, v73
	v_max3_f32 v107, v107, v71, v90
	v_max3_f32 v108, v108, v92, v93
	v_max3_f32 v107, v107, v91, v74
	v_max3_f32 v108, v108, v76, v77
	v_max3_f32 v107, v107, v75, v94
	v_max3_f32 v108, v108, v96, v97
	v_max3_f32 v107, v107, v95, v78
	v_max3_f32 v108, v108, v80, v81
	v_add_f32_e32 v222, v208, v106
	v_max3_f32 v106, v107, v79, v108
	v_mov_b32_e32 v107, v106
	s_nop 1
	v_permlane32_swap_b32_e32 v106, v107
	v_max_f32_e32 v107, v107, v107
	v_max_f32_e32 v106, v106, v106
	s_add_i32 s3, s63, s49
	s_mov_b32 s6, m0
	s_mov_b32 m0, s3
	s_nop 0
	global_load_lds_dwordx4 v[204:205], off
	s_mov_b32 m0, s6
	v_max_f32_e32 v106, v106, v107
	s_add_i32 s3, s62, s61
	s_mov_b32 s6, m0
	s_mov_b32 m0, s3
	s_nop 0
	global_load_lds_dwordx4 v[202:203], off
	s_mov_b32 m0, s6
	v_cmp_lt_f32_e32 vcc, s33, v106
	s_cmp_lg_u64 vcc, 0
	s_cselect_b64 s[6:7], -1, 0
	s_cbranch_vccnz .LBB0_509

.LBB0_514:
	v_add_u32_e32 v194, s66, v220
	ds_read_b64_tr_b16 v[126:127], v194 offset:24576
	ds_read_b64_tr_b16 v[128:129], v194 offset:25088
	v_add_f32_e32 v98, v82, v83
	v_add_f32_e32 v98, v84, v98
	v_add_f32_e32 v98, v85, v98
	v_add_f32_e32 v98, v86, v98
	v_add_f32_e32 v114, v87, v98
	s_waitcnt lgkmcnt(9)
	v_mfma_f32_32x32x16_bf16 v[98:113], v[190:193], v[150:153], v[50:65]
	v_cvt_pk_bf16_f32 v158, v82, v83
	v_cvt_pk_bf16_f32 v159, v84, v85
	ds_read_b64_tr_b16 v[122:123], v194 offset:28672
	ds_read_b64_tr_b16 v[124:125], v194 offset:29184
	s_waitcnt lgkmcnt(10)
	v_mfma_f32_32x32x16_bf16 v[50:65], v[186:189], v[150:153], v[50:65]
	v_add_f32_e32 v82, v88, v114
	v_add_f32_e32 v82, v89, v82
	v_add_f32_e32 v82, v90, v82
	v_add_f32_e32 v82, v91, v82
	v_cvt_pk_bf16_f32 v160, v86, v87
	v_cvt_pk_bf16_f32 v161, v88, v89
	ds_read_b64_tr_b16 v[118:119], v194 offset:25600
	ds_read_b64_tr_b16 v[120:121], v194 offset:26112
	s_waitcnt lgkmcnt(11)
	v_mfma_f32_32x32x16_bf16 v[98:113], v[182:185], v[142:145], v[98:113]
	v_add_f32_e32 v82, v92, v82
	v_add_f32_e32 v82, v93, v82
	v_add_f32_e32 v82, v94, v82
	v_add_f32_e32 v82, v95, v82
	v_cvt_pk_bf16_f32 v154, v90, v91
	v_cvt_pk_bf16_f32 v155, v92, v93
	ds_read_b64_tr_b16 v[114:115], v194 offset:29696
	ds_read_b64_tr_b16 v[116:117], v194 offset:30208
	s_waitcnt lgkmcnt(12)
	v_mfma_f32_32x32x16_bf16 v[50:65], v[178:181], v[142:145], v[50:65]
	v_add_f32_e32 v82, v96, v82
	v_add_f32_e32 v82, v97, v82
	v_add_f32_e32 v82, v66, v82
	v_add_f32_e32 v82, v67, v82
	v_cvt_pk_bf16_f32 v156, v94, v95
	v_cvt_pk_bf16_f32 v157, v96, v97
	ds_read_b64_tr_b16 v[94:95], v194 offset:26624
	ds_read_b64_tr_b16 v[96:97], v194 offset:27136
	s_waitcnt lgkmcnt(13)
	v_mfma_f32_32x32x16_bf16 v[98:113], v[174:177], v[134:137], v[98:113]
	v_add_f32_e32 v82, v68, v82
	v_add_f32_e32 v82, v69, v82
	v_add_f32_e32 v82, v70, v82
	v_add_f32_e32 v82, v71, v82
	v_cvt_pk_bf16_f32 v146, v66, v67
	v_cvt_pk_bf16_f32 v147, v68, v69
	ds_read_b64_tr_b16 v[90:91], v194 offset:30720
	ds_read_b64_tr_b16 v[92:93], v194 offset:31232
	s_waitcnt lgkmcnt(14)
	v_mfma_f32_32x32x16_bf16 v[50:65], v[170:173], v[134:137], v[50:65]
	v_add_f32_e32 v66, v72, v82
	v_add_f32_e32 v66, v73, v66
	v_add_f32_e32 v66, v74, v66
	v_add_f32_e32 v66, v75, v66
	v_cvt_pk_bf16_f32 v148, v70, v71
	v_cvt_pk_bf16_f32 v149, v72, v73
	ds_read_b64_tr_b16 v[86:87], v194 offset:27648
	ds_read_b64_tr_b16 v[88:89], v194 offset:28160
	s_waitcnt lgkmcnt(14)
	v_mfma_f32_32x32x16_bf16 v[98:113], v[166:169], v[130:133], v[98:113]
	v_add_f32_e32 v66, v76, v66
	v_add_f32_e32 v66, v77, v66
	v_add_f32_e32 v66, v78, v66
	v_add_f32_e32 v66, v79, v66
	v_cvt_pk_bf16_f32 v138, v74, v75
	v_cvt_pk_bf16_f32 v139, v76, v77
	ds_read_b64_tr_b16 v[82:83], v194 offset:31744
	ds_read_b64_tr_b16 v[84:85], v194 offset:32256
	v_mfma_f32_32x32x16_bf16 v[50:65], v[162:165], v[130:133], v[50:65]
	v_add_f32_e32 v66, v80, v66
	v_add_f32_e32 v66, v81, v66
	v_add_f32_e32 v66, 0, v66
	v_cvt_pk_bf16_f32 v140, v78, v79
	v_cvt_pk_bf16_f32 v141, v80, v81
	s_nop 0
	s_nop 0
	v_max_f32_e32 v67, v98, v99
	s_nop 3
	v_max3_f32 v68, v100, v101, v51
	v_max3_f32 v67, v67, v50, v52
	v_max3_f32 v67, v67, v53, v102
	v_max3_f32 v68, v68, v104, v105
	v_max3_f32 v67, v67, v103, v54
	v_max3_f32 v68, v68, v56, v57
	v_max3_f32 v67, v67, v55, v106
	v_max3_f32 v68, v68, v108, v109
	v_max3_f32 v67, v67, v107, v58
	v_max3_f32 v68, v68, v60, v61
	v_max3_f32 v67, v67, v59, v110
	v_max3_f32 v68, v68, v112, v113
	v_max3_f32 v67, v67, v111, v62
	v_max3_f32 v68, v68, v64, v65
	v_add_f32_e32 v130, v222, v66
	v_max3_f32 v66, v67, v63, v68
	v_mov_b32_e32 v67, v66
	s_nop 1
	v_permlane32_swap_b32_e32 v66, v67
	s_nop 0
	s_nop 0
	v_max_f32_e32 v66, v66, v67
	v_cmp_lt_f32_e32 vcc, s33, v66
	s_cmp_lg_u64 vcc, 0
	s_cselect_b64 s[0:1], -1, 0
	s_cbranch_vccnz .LBB0_565

.LBB0_523:
	v_add_f32_e32 v222, v222, v74
	s_nop 0
	s_nop 0
	v_max_f32_e32 v74, v114, v115
	v_max3_f32 v75, v116, v117, v99
	v_max3_f32 v74, v74, v98, v100
	v_max3_f32 v74, v74, v101, v118
	v_max3_f32 v75, v75, v120, v121
	v_max3_f32 v74, v74, v119, v102
	v_max3_f32 v75, v75, v104, v105
	v_max3_f32 v74, v74, v103, v122
	v_max3_f32 v75, v75, v124, v125
	v_max3_f32 v74, v74, v123, v106
	v_max3_f32 v75, v75, v108, v109
	v_max3_f32 v74, v74, v107, v126
	v_max3_f32 v75, v75, v128, v129
	v_max3_f32 v74, v74, v127, v110
	v_max3_f32 v75, v75, v112, v113
	v_max3_f32 v74, v74, v111, v75
	v_mov_b32_e32 v75, v74
	s_nop 1
	v_permlane32_swap_b32_e32 v74, v75
	s_nop 0
	s_nop 0
	v_max_f32_e32 v74, v74, v75
	s_add_i32 s0, s66, s61
	s_mov_b32 s1, m0
	s_mov_b32 m0, s0
	s_nop 0
	global_load_lds_dwordx4 v[208:209], off
	s_mov_b32 m0, s1
	v_cmp_lt_f32_e32 vcc, s33, v74
	s_cmp_lg_u64 vcc, 0
	s_cselect_b64 s[0:1], -1, 0
	s_cbranch_vccnz .LBB0_559

.LBB0_532:
	v_add_f32_e32 v222, v222, v106
	s_nop 0
	s_nop 0
	v_max_f32_e32 v106, v82, v83
	v_max3_f32 v107, v84, v85, v67
	v_max3_f32 v106, v106, v66, v68
	v_max3_f32 v106, v106, v69, v86
	v_max3_f32 v107, v107, v88, v89
	v_max3_f32 v106, v106, v87, v70
	v_max3_f32 v107, v107, v72, v73
	v_max3_f32 v106, v106, v71, v90
	v_max3_f32 v107, v107, v92, v93
	v_max3_f32 v106, v106, v91, v74
	v_max3_f32 v107, v107, v76, v77
	v_max3_f32 v106, v106, v75, v94
	v_max3_f32 v107, v107, v96, v97
	v_max3_f32 v106, v106, v95, v78
	v_max3_f32 v107, v107, v80, v81
	v_max3_f32 v106, v106, v79, v107
	v_mov_b32_e32 v107, v106
	s_nop 1
	v_permlane32_swap_b32_e32 v106, v107
	s_nop 0
	s_nop 0
	v_max_f32_e32 v106, v106, v107
	v_cmp_lt_f32_e32 vcc, s33, v106
	s_cmp_lg_u64 vcc, 0
	s_cselect_b64 s[76:77], -1, 0
	s_cbranch_vccnz .LBB0_562

.LBB0_1278:
	v_add_u32_e32 v199, s38, v219
	ds_read_b64_tr_b16 v[194:195], v199 offset:24576
	ds_read_b64_tr_b16 v[196:197], v199 offset:25088
	s_waitcnt lgkmcnt(9)
	v_mfma_f32_32x32x16_bf16 v[114:129], v[98:101], v[170:173], v[50:65]
	v_add_f32_e32 v102, v82, v83
	v_add_f32_e32 v102, v84, v102
	v_add_f32_e32 v102, v85, v102
	v_add_f32_e32 v102, v86, v102
	v_add_f32_e32 v102, v87, v102
	v_cvt_pk_bf16_f32 v174, v82, v83
	v_cvt_pk_bf16_f32 v175, v84, v85
	ds_read_b64_tr_b16 v[190:191], v199 offset:28672
	ds_read_b64_tr_b16 v[192:193], v199 offset:29184
	v_add_f32_e32 v82, v88, v102
	s_waitcnt lgkmcnt(10)
	v_mfma_f32_32x32x16_bf16 v[98:113], v[186:189], v[170:173], v[50:65]
	v_add_f32_e32 v82, v89, v82
	v_add_f32_e32 v82, v90, v82
	v_add_f32_e32 v82, v91, v82
	v_cvt_pk_bf16_f32 v176, v86, v87
	v_cvt_pk_bf16_f32 v177, v88, v89
	ds_read_b64_tr_b16 v[186:187], v199 offset:25600
	ds_read_b64_tr_b16 v[188:189], v199 offset:26112
	s_waitcnt lgkmcnt(11)
	v_mfma_f32_32x32x16_bf16 v[114:129], v[182:185], v[162:165], v[114:129]
	v_add_f32_e32 v82, v92, v82
	v_add_f32_e32 v82, v93, v82
	v_add_f32_e32 v82, v94, v82
	v_add_f32_e32 v82, v95, v82
	v_cvt_pk_bf16_f32 v166, v90, v91
	v_cvt_pk_bf16_f32 v167, v92, v93
	ds_read_b64_tr_b16 v[90:91], v199 offset:29696
	ds_read_b64_tr_b16 v[92:93], v199 offset:30208
	s_waitcnt lgkmcnt(12)
	v_mfma_f32_32x32x16_bf16 v[98:113], v[178:181], v[162:165], v[98:113]
	v_add_f32_e32 v82, v96, v82
	v_add_f32_e32 v82, v97, v82
	v_add_f32_e32 v82, v66, v82
	v_add_f32_e32 v82, v67, v82
	v_cvt_pk_bf16_f32 v168, v94, v95
	v_cvt_pk_bf16_f32 v169, v96, v97
	ds_read_b64_tr_b16 v[86:87], v199 offset:26624
	ds_read_b64_tr_b16 v[88:89], v199 offset:27136
	s_waitcnt lgkmcnt(13)
	v_mfma_f32_32x32x16_bf16 v[114:129], v[142:145], v[154:157], v[114:129]
	v_add_f32_e32 v82, v68, v82
	v_add_f32_e32 v82, v69, v82
	v_add_f32_e32 v82, v70, v82
	v_add_f32_e32 v94, v71, v82
	v_cvt_pk_bf16_f32 v158, v66, v67
	v_cvt_pk_bf16_f32 v159, v68, v69
	ds_read_b64_tr_b16 v[82:83], v199 offset:30720
	ds_read_b64_tr_b16 v[84:85], v199 offset:31232
	s_waitcnt lgkmcnt(14)
	v_mfma_f32_32x32x16_bf16 v[98:113], v[138:141], v[154:157], v[98:113]
	v_add_f32_e32 v66, v72, v94
	v_add_f32_e32 v66, v73, v66
	v_add_f32_e32 v66, v74, v66
	v_add_f32_e32 v66, v75, v66
	v_cvt_pk_bf16_f32 v160, v70, v71
	v_cvt_pk_bf16_f32 v161, v72, v73
	ds_read_b64_tr_b16 v[70:71], v199 offset:27648
	ds_read_b64_tr_b16 v[72:73], v199 offset:28160
	s_waitcnt lgkmcnt(14)
	v_mfma_f32_32x32x16_bf16 v[114:129], v[134:137], v[146:149], v[114:129]
	v_add_f32_e32 v66, v76, v66
	v_add_f32_e32 v66, v77, v66
	v_add_f32_e32 v66, v78, v66
	v_add_f32_e32 v94, v79, v66
	v_cvt_pk_bf16_f32 v150, v74, v75
	v_cvt_pk_bf16_f32 v151, v76, v77
	ds_read_b64_tr_b16 v[66:67], v199 offset:31744
	ds_read_b64_tr_b16 v[68:69], v199 offset:32256
	v_mfma_f32_32x32x16_bf16 v[98:113], v[130:133], v[146:149], v[98:113]
	v_add_f32_e32 v74, v80, v94
	v_add_f32_e32 v74, v81, v74
	v_add_f32_e32 v76, 0, v74
	v_cvt_pk_bf16_f32 v152, v78, v79
	v_cvt_pk_bf16_f32 v153, v80, v81
	v_lshl_add_u64 v[74:75], v[204:205], 0, s[20:21]
	s_add_i32 s3, s12, s53
	s_mov_b32 s13, m0
	s_mov_b32 m0, s3
	s_nop 0
	global_load_lds_dwordx4 v[74:75], off
	s_mov_b32 m0, s13
	v_lshl_add_u64 v[74:75], v[202:203], 0, s[20:21]
	s_add_i32 s3, s55, s51
	s_mov_b32 s13, m0
	s_mov_b32 m0, s3
	s_nop 0
	global_load_lds_dwordx4 v[74:75], off
	s_mov_b32 m0, s13
	s_nop 0
	s_nop 0
	v_max_f32_e32 v74, v114, v115
	v_max3_f32 v75, v116, v117, v99
	v_max3_f32 v74, v74, v98, v100
	v_max3_f32 v74, v74, v101, v118
	v_max3_f32 v75, v75, v120, v121
	v_max3_f32 v74, v74, v119, v102
	v_max3_f32 v75, v75, v104, v105
	v_max3_f32 v74, v74, v103, v122
	v_max3_f32 v75, v75, v124, v125
	v_max3_f32 v74, v74, v123, v106
	v_max3_f32 v75, v75, v108, v109
	v_max3_f32 v74, v74, v107, v126
	v_max3_f32 v75, v75, v128, v129
	v_max3_f32 v74, v74, v127, v110
	v_max3_f32 v75, v75, v112, v113
	v_max3_f32 v74, v74, v111, v75
	v_mov_b32_e32 v75, v74
	s_nop 1
	v_permlane32_swap_b32_e32 v74, v75
	s_nop 0
	s_nop 0
	v_max_f32_e32 v74, v74, v75
	v_cmp_lt_f32_e32 vcc, s48, v74
	s_cmp_lg_u64 vcc, 0
	v_add_f32_e32 v222, v198, v76
	s_cselect_b64 s[38:39], -1, 0
	s_cbranch_vccnz .LBB0_1286

.LBB0_1281:
	s_add_i32 s3, s55, 0x2000
	s_cmpk_lg_i32 s55, 0x4000
	s_cselect_b32 s13, s3, 0
	v_add_u32_e32 v223, s12, v219
	ds_read_b64_tr_b16 v[142:143], v223 offset:24576
	ds_read_b64_tr_b16 v[144:145], v223 offset:25088
	s_waitcnt lgkmcnt(9)
	v_mfma_f32_32x32x16_bf16 v[82:97], v[74:77], v[170:173], v[50:65]
	v_add_f32_e32 v66, v114, v115
	v_add_f32_e32 v66, v116, v66
	v_add_f32_e32 v66, v117, v66
	v_add_f32_e32 v66, v118, v66
	v_add_f32_e32 v66, v119, v66
	v_cvt_pk_bf16_f32 v174, v114, v115
	v_cvt_pk_bf16_f32 v175, v116, v117
	ds_read_b64_tr_b16 v[138:139], v223 offset:28672
	ds_read_b64_tr_b16 v[140:141], v223 offset:29184
	v_add_f32_e32 v66, v120, v66
	v_add_f32_e32 v66, v121, v66
	v_add_f32_e32 v66, v122, v66
	v_add_f32_e32 v114, v123, v66
	s_waitcnt lgkmcnt(10)
	v_mfma_f32_32x32x16_bf16 v[66:81], v[130:133], v[170:173], v[50:65]
	v_cvt_pk_bf16_f32 v176, v118, v119
	v_cvt_pk_bf16_f32 v177, v120, v121
	ds_read_b64_tr_b16 v[134:135], v223 offset:25600
	ds_read_b64_tr_b16 v[136:137], v223 offset:26112
	s_waitcnt lgkmcnt(11)
	v_mfma_f32_32x32x16_bf16 v[82:97], v[198:201], v[162:165], v[82:97]
	v_add_f32_e32 v114, v124, v114
	v_add_f32_e32 v114, v125, v114
	v_add_f32_e32 v114, v126, v114
	v_add_f32_e32 v114, v127, v114
	v_cvt_pk_bf16_f32 v166, v122, v123
	v_cvt_pk_bf16_f32 v167, v124, v125
	ds_read_b64_tr_b16 v[130:131], v223 offset:29696
	ds_read_b64_tr_b16 v[132:133], v223 offset:30208
	s_waitcnt lgkmcnt(12)
	v_mfma_f32_32x32x16_bf16 v[66:81], v[190:193], v[162:165], v[66:81]
	v_add_f32_e32 v114, v128, v114
	v_add_f32_e32 v114, v129, v114
	v_add_f32_e32 v114, v98, v114
	v_add_f32_e32 v114, v99, v114
	v_cvt_pk_bf16_f32 v168, v126, v127
	v_cvt_pk_bf16_f32 v169, v128, v129
	ds_read_b64_tr_b16 v[122:123], v223 offset:26624
	ds_read_b64_tr_b16 v[124:125], v223 offset:27136
	s_waitcnt lgkmcnt(13)
	v_mfma_f32_32x32x16_bf16 v[82:97], v[194:197], v[154:157], v[82:97]
	v_add_f32_e32 v114, v100, v114
	v_add_f32_e32 v114, v101, v114
	v_add_f32_e32 v114, v102, v114
	v_add_f32_e32 v114, v103, v114
	v_cvt_pk_bf16_f32 v158, v98, v99
	v_cvt_pk_bf16_f32 v159, v100, v101
	ds_read_b64_tr_b16 v[118:119], v223 offset:30720
	ds_read_b64_tr_b16 v[120:121], v223 offset:31232
	s_waitcnt lgkmcnt(14)
	v_mfma_f32_32x32x16_bf16 v[66:81], v[182:185], v[154:157], v[66:81]
	v_add_f32_e32 v98, v104, v114
	v_add_f32_e32 v98, v105, v98
	v_add_f32_e32 v98, v106, v98
	v_add_f32_e32 v98, v107, v98
	v_cvt_pk_bf16_f32 v160, v102, v103
	v_cvt_pk_bf16_f32 v161, v104, v105
	ds_read_b64_tr_b16 v[114:115], v223 offset:27648
	ds_read_b64_tr_b16 v[116:117], v223 offset:28160
	s_waitcnt lgkmcnt(14)
	v_mfma_f32_32x32x16_bf16 v[82:97], v[186:189], v[146:149], v[82:97]
	v_add_f32_e32 v98, v108, v98
	v_add_f32_e32 v98, v109, v98
	v_add_f32_e32 v98, v110, v98
	v_add_f32_e32 v98, v111, v98
	v_cvt_pk_bf16_f32 v150, v106, v107
	v_cvt_pk_bf16_f32 v151, v108, v109
	ds_read_b64_tr_b16 v[102:103], v223 offset:31744
	ds_read_b64_tr_b16 v[104:105], v223 offset:32256
	v_mfma_f32_32x32x16_bf16 v[66:81], v[178:181], v[146:149], v[66:81]
	v_add_f32_e32 v98, v112, v98
	v_add_f32_e32 v98, v113, v98
	v_add_f32_e32 v98, 0, v98
	v_cvt_pk_bf16_f32 v152, v110, v111
	v_cvt_pk_bf16_f32 v153, v112, v113
	s_nop 0
	s_nop 0
	v_max_f32_e32 v99, v82, v83
	s_nop 3
	v_max3_f32 v100, v84, v85, v67
	v_max3_f32 v99, v99, v66, v68
	v_max3_f32 v99, v99, v69, v86
	v_max3_f32 v100, v100, v88, v89
	v_max3_f32 v99, v99, v87, v70
	v_max3_f32 v100, v100, v72, v73
	v_max3_f32 v99, v99, v71, v90
	v_max3_f32 v100, v100, v92, v93
	v_max3_f32 v99, v99, v91, v74
	v_max3_f32 v100, v100, v76, v77
	v_max3_f32 v99, v99, v75, v94
	v_max3_f32 v100, v100, v96, v97
	v_max3_f32 v99, v99, v95, v78
	v_max3_f32 v100, v100, v80, v81
	v_add_f32_e32 v198, v222, v98
	v_max3_f32 v98, v99, v79, v100
	v_mov_b32_e32 v99, v98
	s_nop 1
	v_permlane32_swap_b32_e32 v98, v99
	v_max_f32_e32 v99, v99, v99
	v_max_f32_e32 v98, v98, v98
	s_add_i32 s3, s55, s53
	s_mov_b32 s12, m0
	s_mov_b32 m0, s3
	s_nop 0
	global_load_lds_dwordx4 v[204:205], off
	s_mov_b32 m0, s12
	v_max_f32_e32 v98, v98, v99
	s_add_i32 s3, s13, s51
	s_mov_b32 s12, m0
	s_mov_b32 m0, s3
	s_nop 0
	global_load_lds_dwordx4 v[202:203], off
	s_mov_b32 m0, s12
	v_cmp_lt_f32_e32 vcc, s48, v98
	s_cmp_lg_u64 vcc, 0
	s_cselect_b64 s[38:39], -1, 0
	s_cbranch_vccnz .LBB0_1289

.LBB0_1292:
	ds_read_b64_tr_b16 v[194:195], v219 offset:24576
	ds_read_b64_tr_b16 v[196:197], v219 offset:25088
	s_waitcnt lgkmcnt(9)
	v_mfma_f32_32x32x16_bf16 v[114:129], v[98:101], v[170:173], v[50:65]
	v_add_f32_e32 v102, v82, v83
	v_add_f32_e32 v102, v84, v102
	v_add_f32_e32 v102, v85, v102
	v_add_f32_e32 v102, v86, v102
	v_add_f32_e32 v102, v87, v102
	v_cvt_pk_bf16_f32 v174, v82, v83
	v_cvt_pk_bf16_f32 v175, v84, v85
	ds_read_b64_tr_b16 v[190:191], v219 offset:28672
	ds_read_b64_tr_b16 v[192:193], v219 offset:29184
	v_add_f32_e32 v82, v88, v102
	s_waitcnt lgkmcnt(10)
	v_mfma_f32_32x32x16_bf16 v[98:113], v[186:189], v[170:173], v[50:65]
	v_add_f32_e32 v82, v89, v82
	v_add_f32_e32 v82, v90, v82
	v_add_f32_e32 v82, v91, v82
	v_cvt_pk_bf16_f32 v176, v86, v87
	v_cvt_pk_bf16_f32 v177, v88, v89
	ds_read_b64_tr_b16 v[186:187], v219 offset:25600
	ds_read_b64_tr_b16 v[188:189], v219 offset:26112
	s_waitcnt lgkmcnt(11)
	v_mfma_f32_32x32x16_bf16 v[114:129], v[182:185], v[162:165], v[114:129]
	v_add_f32_e32 v82, v92, v82
	v_add_f32_e32 v82, v93, v82
	v_add_f32_e32 v82, v94, v82
	v_add_f32_e32 v82, v95, v82
	v_cvt_pk_bf16_f32 v166, v90, v91
	v_cvt_pk_bf16_f32 v167, v92, v93
	ds_read_b64_tr_b16 v[90:91], v219 offset:29696
	ds_read_b64_tr_b16 v[92:93], v219 offset:30208
	s_waitcnt lgkmcnt(12)
	v_mfma_f32_32x32x16_bf16 v[98:113], v[178:181], v[162:165], v[98:113]
	v_add_f32_e32 v82, v96, v82
	v_add_f32_e32 v82, v97, v82
	v_add_f32_e32 v82, v66, v82
	v_add_f32_e32 v82, v67, v82
	v_cvt_pk_bf16_f32 v168, v94, v95
	v_cvt_pk_bf16_f32 v169, v96, v97
	ds_read_b64_tr_b16 v[86:87], v219 offset:26624
	ds_read_b64_tr_b16 v[88:89], v219 offset:27136
	s_waitcnt lgkmcnt(13)
	v_mfma_f32_32x32x16_bf16 v[114:129], v[142:145], v[154:157], v[114:129]
	v_add_f32_e32 v82, v68, v82
	v_add_f32_e32 v82, v69, v82
	v_add_f32_e32 v82, v70, v82
	v_add_f32_e32 v94, v71, v82
	v_cvt_pk_bf16_f32 v158, v66, v67
	v_cvt_pk_bf16_f32 v159, v68, v69
	ds_read_b64_tr_b16 v[82:83], v219 offset:30720
	ds_read_b64_tr_b16 v[84:85], v219 offset:31232
	s_waitcnt lgkmcnt(14)
	v_mfma_f32_32x32x16_bf16 v[98:113], v[138:141], v[154:157], v[98:113]
	v_add_f32_e32 v66, v72, v94
	v_add_f32_e32 v66, v73, v66
	v_add_f32_e32 v66, v74, v66
	v_add_f32_e32 v66, v75, v66
	v_cvt_pk_bf16_f32 v160, v70, v71
	v_cvt_pk_bf16_f32 v161, v72, v73
	ds_read_b64_tr_b16 v[70:71], v219 offset:27648
	ds_read_b64_tr_b16 v[72:73], v219 offset:28160
	s_waitcnt lgkmcnt(14)
	v_mfma_f32_32x32x16_bf16 v[114:129], v[134:137], v[146:149], v[114:129]
	v_add_f32_e32 v66, v76, v66
	v_add_f32_e32 v66, v77, v66
	v_add_f32_e32 v66, v78, v66
	v_add_f32_e32 v94, v79, v66
	v_cvt_pk_bf16_f32 v150, v74, v75
	v_cvt_pk_bf16_f32 v151, v76, v77
	ds_read_b64_tr_b16 v[66:67], v219 offset:31744
	ds_read_b64_tr_b16 v[68:69], v219 offset:32256
	v_mfma_f32_32x32x16_bf16 v[98:113], v[130:133], v[146:149], v[98:113]
	v_add_f32_e32 v74, v80, v94
	v_add_f32_e32 v74, v81, v74
	v_add_f32_e32 v74, 0, v74
	v_cvt_pk_bf16_f32 v152, v78, v79
	v_cvt_pk_bf16_f32 v153, v80, v81
	s_cmp_lg_u32 0, -1
	s_cselect_b32 s3, 0, 0
	v_add_f32_e32 v222, v198, v74
	v_lshl_add_u64 v[74:75], v[210:211], 0, s[22:23]
	s_add_i32 s53, s3, s50
	s_add_i32 s3, s53, 0x2000
	s_mov_b32 s12, m0
	s_mov_b32 m0, s3
	s_nop 0
	global_load_lds_dwordx4 v[74:75], off
	s_mov_b32 m0, s12
	v_lshl_add_u64 v[74:75], v[208:209], 0, s[24:25]
	s_add_i32 s53, s53, 0xa000
	s_mov_b32 s3, m0
	s_mov_b32 m0, s53
	s_nop 0
	global_load_lds_dwordx4 v[74:75], off
	s_mov_b32 m0, s3
	s_nop 0
	s_nop 0
	v_max_f32_e32 v74, v114, v115
	v_max3_f32 v75, v116, v117, v99
	v_max3_f32 v74, v74, v98, v100
	v_max3_f32 v74, v74, v101, v118
	v_max3_f32 v75, v75, v120, v121
	v_max3_f32 v74, v74, v119, v102
	v_max3_f32 v75, v75, v104, v105
	v_max3_f32 v74, v74, v103, v122
	v_max3_f32 v75, v75, v124, v125
	v_max3_f32 v74, v74, v123, v106
	v_max3_f32 v75, v75, v108, v109
	v_max3_f32 v74, v74, v107, v126
	v_max3_f32 v75, v75, v128, v129
	v_max3_f32 v74, v74, v127, v110
	v_max3_f32 v75, v75, v112, v113
	v_max3_f32 v74, v74, v111, v75
	v_mov_b32_e32 v75, v74
	s_nop 1
	v_permlane32_swap_b32_e32 v74, v75
	s_nop 0
	s_nop 0
	v_max_f32_e32 v74, v74, v75
	v_cmp_lt_f32_e32 vcc, s48, v74
	s_cmp_lg_u64 vcc, 0
	s_cselect_b64 s[38:39], -1, 0
	s_cbranch_vccnz .LBB0_1309

.LBB0_1295:
	ds_read_b64_tr_b16 v[182:183], v219 offset:32768
	ds_read_b64_tr_b16 v[184:185], v219 offset:33280
	s_waitcnt lgkmcnt(9)
	v_mfma_f32_32x32x16_bf16 v[130:145], v[74:77], v[170:173], v[50:65]
	v_add_f32_e32 v66, v114, v115
	v_add_f32_e32 v66, v116, v66
	v_add_f32_e32 v66, v117, v66
	v_add_f32_e32 v66, v118, v66
	v_add_f32_e32 v66, v119, v66
	v_cvt_pk_bf16_f32 v174, v114, v115
	v_cvt_pk_bf16_f32 v175, v116, v117
	ds_read_b64_tr_b16 v[178:179], v219 offset:36864
	ds_read_b64_tr_b16 v[180:181], v219 offset:37376
	v_add_f32_e32 v66, v120, v66
	v_add_f32_e32 v66, v121, v66
	v_add_f32_e32 v66, v122, v66
	v_add_f32_e32 v82, v123, v66
	s_waitcnt lgkmcnt(10)
	v_mfma_f32_32x32x16_bf16 v[66:81], v[198:201], v[170:173], v[50:65]
	v_cvt_pk_bf16_f32 v176, v118, v119
	v_cvt_pk_bf16_f32 v177, v120, v121
	ds_read_b64_tr_b16 v[118:119], v219 offset:33792
	ds_read_b64_tr_b16 v[120:121], v219 offset:34304
	s_waitcnt lgkmcnt(11)
	v_mfma_f32_32x32x16_bf16 v[130:145], v[202:205], v[162:165], v[130:145]
	v_add_f32_e32 v82, v124, v82
	v_add_f32_e32 v82, v125, v82
	v_add_f32_e32 v82, v126, v82
	v_add_f32_e32 v82, v127, v82
	v_cvt_pk_bf16_f32 v166, v122, v123
	v_cvt_pk_bf16_f32 v167, v124, v125
	ds_read_b64_tr_b16 v[114:115], v219 offset:37888
	ds_read_b64_tr_b16 v[116:117], v219 offset:38400
	s_waitcnt lgkmcnt(12)
	v_mfma_f32_32x32x16_bf16 v[66:81], v[94:97], v[162:165], v[66:81]
	v_add_f32_e32 v82, v128, v82
	v_add_f32_e32 v82, v129, v82
	v_add_f32_e32 v82, v98, v82
	v_add_f32_e32 v82, v99, v82
	v_cvt_pk_bf16_f32 v168, v126, v127
	v_cvt_pk_bf16_f32 v169, v128, v129
	ds_read_b64_tr_b16 v[94:95], v219 offset:34816
	ds_read_b64_tr_b16 v[96:97], v219 offset:35328
	s_waitcnt lgkmcnt(13)
	v_mfma_f32_32x32x16_bf16 v[130:145], v[90:93], v[154:157], v[130:145]
	v_add_f32_e32 v82, v100, v82
	v_add_f32_e32 v82, v101, v82
	v_add_f32_e32 v82, v102, v82
	v_add_f32_e32 v82, v103, v82
	v_cvt_pk_bf16_f32 v158, v98, v99
	v_cvt_pk_bf16_f32 v159, v100, v101
	ds_read_b64_tr_b16 v[90:91], v219 offset:38912
	ds_read_b64_tr_b16 v[92:93], v219 offset:39424
	s_waitcnt lgkmcnt(14)
	v_mfma_f32_32x32x16_bf16 v[66:81], v[190:193], v[154:157], v[66:81]
	v_add_f32_e32 v82, v104, v82
	v_add_f32_e32 v82, v105, v82
	v_add_f32_e32 v82, v106, v82
	v_add_f32_e32 v82, v107, v82
	v_cvt_pk_bf16_f32 v160, v102, v103
	v_cvt_pk_bf16_f32 v161, v104, v105
	ds_read_b64_tr_b16 v[86:87], v219 offset:35840
	ds_read_b64_tr_b16 v[88:89], v219 offset:36352
	s_waitcnt lgkmcnt(14)
	v_mfma_f32_32x32x16_bf16 v[130:145], v[194:197], v[146:149], v[130:145]
	v_add_f32_e32 v82, v108, v82
	v_add_f32_e32 v82, v109, v82
	v_add_f32_e32 v82, v110, v82
	v_add_f32_e32 v98, v111, v82
	v_cvt_pk_bf16_f32 v150, v106, v107
	v_cvt_pk_bf16_f32 v151, v108, v109
	ds_read_b64_tr_b16 v[82:83], v219 offset:39936
	ds_read_b64_tr_b16 v[84:85], v219 offset:40448
	v_mfma_f32_32x32x16_bf16 v[66:81], v[186:189], v[146:149], v[66:81]
	v_add_f32_e32 v98, v112, v98
	v_add_f32_e32 v98, v113, v98
	v_add_f32_e32 v98, 0, v98
	v_cvt_pk_bf16_f32 v152, v110, v111
	v_cvt_pk_bf16_f32 v153, v112, v113
	s_cmp_lg_u32 0, -1
	s_cselect_b32 s3, 0, 0
	v_add_f32_e32 v198, v222, v98
	v_lshl_add_u64 v[98:99], v[210:211], 0, s[26:27]
	s_add_i32 s3, s3, s50
	s_addk_i32 s3, 0x4000
	s_mov_b32 s12, m0
	s_mov_b32 m0, s3
	s_nop 0
	global_load_lds_dwordx4 v[98:99], off
	s_mov_b32 m0, s12
	v_lshl_add_u64 v[98:99], v[208:209], 0, s[28:29]
	s_mov_b32 s3, m0
	s_mov_b32 m0, s51
	s_nop 0
	global_load_lds_dwordx4 v[98:99], off
	s_mov_b32 m0, s3
	s_nop 0
	s_nop 0
	v_max_f32_e32 v98, v130, v131
	v_max3_f32 v99, v132, v133, v67
	v_max3_f32 v98, v98, v66, v68
	v_max3_f32 v98, v98, v69, v134
	v_max3_f32 v99, v99, v136, v137
	v_max3_f32 v98, v98, v135, v70
	v_max3_f32 v99, v99, v72, v73
	v_max3_f32 v98, v98, v71, v138
	v_max3_f32 v99, v99, v140, v141
	v_max3_f32 v98, v98, v139, v74
	v_max3_f32 v99, v99, v76, v77
	v_max3_f32 v98, v98, v75, v142
	v_max3_f32 v99, v99, v144, v145
	v_max3_f32 v98, v98, v143, v78
	v_max3_f32 v99, v99, v80, v81
	v_max3_f32 v98, v98, v79, v99
	v_mov_b32_e32 v99, v98
	s_nop 1
	v_permlane32_swap_b32_e32 v98, v99
	s_nop 0
	s_nop 0
	v_max_f32_e32 v98, v98, v99
	v_cmp_lt_f32_e32 vcc, s48, v98
	s_cmp_lg_u64 vcc, 0
	s_cselect_b64 s[38:39], -1, 0
	s_cbranch_vccnz .LBB0_1312

.LBB0_1298:
	ds_read_b64_tr_b16 v[178:179], v219 offset:40960
	ds_read_b64_tr_b16 v[180:181], v219 offset:41472
	s_waitcnt lgkmcnt(9)
	v_mfma_f32_32x32x16_bf16 v[98:113], v[126:129], v[170:173], v[50:65]
	v_add_f32_e32 v82, v130, v131
	v_add_f32_e32 v82, v132, v82
	v_add_f32_e32 v82, v133, v82
	v_add_f32_e32 v82, v134, v82
	v_add_f32_e32 v82, v135, v82
	v_cvt_pk_bf16_f32 v174, v130, v131
	v_cvt_pk_bf16_f32 v175, v132, v133
	ds_read_b64_tr_b16 v[130:131], v219 offset:45056
	ds_read_b64_tr_b16 v[132:133], v219 offset:45568
	v_add_f32_e32 v82, v136, v82
	v_add_f32_e32 v82, v137, v82
	v_add_f32_e32 v82, v138, v82
	v_add_f32_e32 v150, v139, v82
	s_waitcnt lgkmcnt(10)
	v_mfma_f32_32x32x16_bf16 v[82:97], v[122:125], v[170:173], v[50:65]
	v_cvt_pk_bf16_f32 v176, v134, v135
	v_cvt_pk_bf16_f32 v177, v136, v137
	ds_read_b64_tr_b16 v[126:127], v219 offset:41984
	ds_read_b64_tr_b16 v[128:129], v219 offset:42496
	s_waitcnt lgkmcnt(11)
	v_mfma_f32_32x32x16_bf16 v[98:113], v[194:197], v[162:165], v[98:113]
	v_add_f32_e32 v122, v140, v150
	v_add_f32_e32 v122, v141, v122
	v_add_f32_e32 v122, v142, v122
	v_add_f32_e32 v134, v143, v122
	v_cvt_pk_bf16_f32 v166, v138, v139
	v_cvt_pk_bf16_f32 v167, v140, v141
	ds_read_b64_tr_b16 v[122:123], v219 offset:46080
	ds_read_b64_tr_b16 v[124:125], v219 offset:46592
	s_waitcnt lgkmcnt(12)
	v_mfma_f32_32x32x16_bf16 v[82:97], v[118:121], v[162:165], v[82:97]
	v_add_f32_e32 v134, v144, v134
	v_add_f32_e32 v134, v145, v134
	v_add_f32_e32 v134, v66, v134
	v_add_f32_e32 v134, v67, v134
	v_cvt_pk_bf16_f32 v168, v142, v143
	v_cvt_pk_bf16_f32 v169, v144, v145
	ds_read_b64_tr_b16 v[118:119], v219 offset:43008
	ds_read_b64_tr_b16 v[120:121], v219 offset:43520
	s_waitcnt lgkmcnt(13)
	v_mfma_f32_32x32x16_bf16 v[98:113], v[114:117], v[154:157], v[98:113]
	v_add_f32_e32 v134, v68, v134
	v_add_f32_e32 v134, v69, v134
	v_add_f32_e32 v134, v70, v134
	v_add_f32_e32 v134, v71, v134
	v_cvt_pk_bf16_f32 v158, v66, v67
	v_cvt_pk_bf16_f32 v159, v68, v69
	ds_read_b64_tr_b16 v[114:115], v219 offset:47104
	ds_read_b64_tr_b16 v[116:117], v219 offset:47616
	s_waitcnt lgkmcnt(14)
	v_mfma_f32_32x32x16_bf16 v[82:97], v[186:189], v[154:157], v[82:97]
	v_add_f32_e32 v66, v72, v134
	v_add_f32_e32 v66, v73, v66
	v_add_f32_e32 v66, v74, v66
	v_add_f32_e32 v66, v75, v66
	v_cvt_pk_bf16_f32 v160, v70, v71
	v_cvt_pk_bf16_f32 v161, v72, v73
	ds_read_b64_tr_b16 v[70:71], v219 offset:44032
	ds_read_b64_tr_b16 v[72:73], v219 offset:44544
	s_waitcnt lgkmcnt(14)
	v_mfma_f32_32x32x16_bf16 v[98:113], v[190:193], v[146:149], v[98:113]
	v_add_f32_e32 v66, v76, v66
	v_add_f32_e32 v66, v77, v66
	v_add_f32_e32 v66, v78, v66
	v_add_f32_e32 v134, v79, v66
	v_cvt_pk_bf16_f32 v150, v74, v75
	v_cvt_pk_bf16_f32 v151, v76, v77
	ds_read_b64_tr_b16 v[66:67], v219 offset:48128
	ds_read_b64_tr_b16 v[68:69], v219 offset:48640
	v_mfma_f32_32x32x16_bf16 v[82:97], v[182:185], v[146:149], v[82:97]
	v_add_f32_e32 v74, v80, v134
	v_add_f32_e32 v74, v81, v74
	v_add_f32_e32 v74, 0, v74
	v_cvt_pk_bf16_f32 v152, v78, v79
	v_cvt_pk_bf16_f32 v153, v80, v81
	s_cmp_lg_u32 0, -1
	s_cselect_b32 s3, 0, 0
	v_add_f32_e32 v198, v198, v74
	v_lshl_add_u64 v[74:75], v[208:209], 0, s[22:23]
	s_add_i32 s3, s3, s50
	s_add_i32 s3, s3, 0x8000
	s_mov_b32 s12, m0
	s_mov_b32 m0, s3
	s_nop 0
	global_load_lds_dwordx4 v[74:75], off
	s_mov_b32 m0, s12
	s_nop 0
	s_nop 0
	v_max_f32_e32 v74, v98, v99
	v_max3_f32 v75, v100, v101, v83
	v_max3_f32 v74, v74, v82, v84
	v_max3_f32 v74, v74, v85, v102
	v_max3_f32 v75, v75, v104, v105
	v_max3_f32 v74, v74, v103, v86
	v_max3_f32 v75, v75, v88, v89
	v_max3_f32 v74, v74, v87, v106
	v_max3_f32 v75, v75, v108, v109
	v_max3_f32 v74, v74, v107, v90
	v_max3_f32 v75, v75, v92, v93
	v_max3_f32 v74, v74, v91, v110
	v_max3_f32 v75, v75, v112, v113
	v_max3_f32 v74, v74, v111, v94
	v_max3_f32 v75, v75, v96, v97
	v_max3_f32 v74, v74, v95, v75
	v_mov_b32_e32 v75, v74
	s_nop 1
	v_permlane32_swap_b32_e32 v74, v75
	s_nop 0
	s_nop 0
	v_max_f32_e32 v74, v74, v75
	v_cmp_lt_f32_e32 vcc, s48, v74
	s_cmp_lg_u64 vcc, 0
	s_cselect_b64 s[38:39], -1, 0
	s_cbranch_vccnz .LBB0_1315

.LBB0_1301:
	ds_read_b64_tr_b16 v[138:139], v219 offset:24576
	ds_read_b64_tr_b16 v[140:141], v219 offset:25088
	s_waitcnt lgkmcnt(9)
	v_mfma_f32_32x32x16_bf16 v[114:129], v[74:77], v[170:173], v[50:65]
	v_add_f32_e32 v66, v98, v99
	v_add_f32_e32 v66, v100, v66
	v_add_f32_e32 v66, v101, v66
	v_add_f32_e32 v66, v102, v66
	v_add_f32_e32 v66, v103, v66
	v_cvt_pk_bf16_f32 v174, v98, v99
	v_cvt_pk_bf16_f32 v175, v100, v101
	ds_read_b64_tr_b16 v[134:135], v219 offset:28672
	ds_read_b64_tr_b16 v[136:137], v219 offset:29184
	v_add_f32_e32 v66, v104, v66
	v_add_f32_e32 v66, v105, v66
	v_add_f32_e32 v66, v106, v66
	v_add_f32_e32 v98, v107, v66
	s_waitcnt lgkmcnt(10)
	v_mfma_f32_32x32x16_bf16 v[66:81], v[130:133], v[170:173], v[50:65]
	v_cvt_pk_bf16_f32 v176, v102, v103
	v_cvt_pk_bf16_f32 v177, v104, v105
	ds_read_b64_tr_b16 v[130:131], v219 offset:25600
	ds_read_b64_tr_b16 v[132:133], v219 offset:26112
	s_waitcnt lgkmcnt(11)
	v_mfma_f32_32x32x16_bf16 v[114:129], v[194:197], v[162:165], v[114:129]
	v_add_f32_e32 v98, v108, v98
	v_add_f32_e32 v98, v109, v98
	v_add_f32_e32 v98, v110, v98
	v_add_f32_e32 v98, v111, v98
	v_cvt_pk_bf16_f32 v166, v106, v107
	v_cvt_pk_bf16_f32 v167, v108, v109
	ds_read_b64_tr_b16 v[106:107], v219 offset:29696
	ds_read_b64_tr_b16 v[108:109], v219 offset:30208
	s_waitcnt lgkmcnt(12)
	v_mfma_f32_32x32x16_bf16 v[66:81], v[186:189], v[162:165], v[66:81]
	v_add_f32_e32 v98, v112, v98
	v_add_f32_e32 v98, v113, v98
	v_add_f32_e32 v98, v82, v98
	v_add_f32_e32 v98, v83, v98
	v_cvt_pk_bf16_f32 v168, v110, v111
	v_cvt_pk_bf16_f32 v169, v112, v113
	ds_read_b64_tr_b16 v[102:103], v219 offset:26624
	ds_read_b64_tr_b16 v[104:105], v219 offset:27136
	s_waitcnt lgkmcnt(13)
	v_mfma_f32_32x32x16_bf16 v[114:129], v[190:193], v[154:157], v[114:129]
	v_add_f32_e32 v98, v84, v98
	v_add_f32_e32 v98, v85, v98
	v_add_f32_e32 v98, v86, v98
	v_add_f32_e32 v110, v87, v98
	v_cvt_pk_bf16_f32 v158, v82, v83
	v_cvt_pk_bf16_f32 v159, v84, v85
	ds_read_b64_tr_b16 v[98:99], v219 offset:30720
	ds_read_b64_tr_b16 v[100:101], v219 offset:31232
	s_waitcnt lgkmcnt(14)
	v_mfma_f32_32x32x16_bf16 v[66:81], v[178:181], v[154:157], v[66:81]
	v_add_f32_e32 v82, v88, v110
	v_add_f32_e32 v82, v89, v82
	v_add_f32_e32 v82, v90, v82
	v_add_f32_e32 v82, v91, v82
	v_cvt_pk_bf16_f32 v160, v86, v87
	v_cvt_pk_bf16_f32 v161, v88, v89
	ds_read_b64_tr_b16 v[86:87], v219 offset:27648
	ds_read_b64_tr_b16 v[88:89], v219 offset:28160
	s_waitcnt lgkmcnt(14)
	v_mfma_f32_32x32x16_bf16 v[114:129], v[182:185], v[146:149], v[114:129]
	v_add_f32_e32 v82, v92, v82
	v_add_f32_e32 v82, v93, v82
	v_add_f32_e32 v82, v94, v82
	v_add_f32_e32 v110, v95, v82
	v_cvt_pk_bf16_f32 v150, v90, v91
	v_cvt_pk_bf16_f32 v151, v92, v93
	ds_read_b64_tr_b16 v[82:83], v219 offset:31744
	ds_read_b64_tr_b16 v[84:85], v219 offset:32256
	v_mfma_f32_32x32x16_bf16 v[66:81], v[142:145], v[146:149], v[66:81]
	v_add_f32_e32 v90, v96, v110
	v_add_f32_e32 v90, v97, v90
	v_add_f32_e32 v90, 0, v90
	v_cvt_pk_bf16_f32 v152, v94, v95
	v_cvt_pk_bf16_f32 v153, v96, v97
	s_nop 0
	v_add_f32_e32 v190, v198, v90
	v_lshl_add_u64 v[90:91], v[208:209], 0, s[26:27]
	s_mov_b32 s3, m0
	s_mov_b32 m0, s53
	s_nop 0
	global_load_lds_dwordx4 v[90:91], off
	s_mov_b32 m0, s3
	s_nop 0
	s_nop 0
	v_max_f32_e32 v90, v114, v115
	s_nop 0
	v_max3_f32 v91, v116, v117, v67
	v_max3_f32 v90, v90, v66, v68
	v_max3_f32 v90, v90, v69, v118
	v_max3_f32 v91, v91, v120, v121
	v_max3_f32 v90, v90, v119, v70
	v_max3_f32 v91, v91, v72, v73
	v_max3_f32 v90, v90, v71, v122
	v_max3_f32 v91, v91, v124, v125
	v_max3_f32 v90, v90, v123, v74
	v_max3_f32 v91, v91, v76, v77
	v_max3_f32 v90, v90, v75, v126
	v_max3_f32 v91, v91, v128, v129
	v_max3_f32 v90, v90, v127, v78
	v_max3_f32 v91, v91, v80, v81
	v_max3_f32 v90, v90, v79, v91
	v_mov_b32_e32 v91, v90
	s_nop 1
	v_permlane32_swap_b32_e32 v90, v91
	s_nop 0
	s_nop 0
	v_max_f32_e32 v90, v90, v91
	v_cmp_lt_f32_e32 vcc, s48, v90
	s_cmp_lg_u64 vcc, 0
	s_cselect_b64 s[38:39], -1, 0
	s_cbranch_vccnz .LBB0_1318

.LBB0_1304:
	ds_read_b64_tr_b16 v[138:139], v219 offset:32768
	ds_read_b64_tr_b16 v[140:141], v219 offset:33280
	v_add_f32_e32 v82, v114, v115
	v_add_f32_e32 v82, v116, v82
	v_add_f32_e32 v82, v117, v82
	v_add_f32_e32 v82, v118, v82
	v_add_f32_e32 v98, v119, v82
	s_waitcnt lgkmcnt(9)
	v_mfma_f32_32x32x16_bf16 v[82:97], v[134:137], v[170:173], v[50:65]
	v_cvt_pk_bf16_f32 v174, v114, v115
	v_cvt_pk_bf16_f32 v175, v116, v117
	ds_read_b64_tr_b16 v[134:135], v219 offset:36864
	ds_read_b64_tr_b16 v[136:137], v219 offset:37376
	s_waitcnt lgkmcnt(10)
	v_mfma_f32_32x32x16_bf16 v[50:65], v[182:185], v[170:173], v[50:65]
	v_add_f32_e32 v98, v120, v98
	v_add_f32_e32 v98, v121, v98
	v_add_f32_e32 v98, v122, v98
	v_add_f32_e32 v98, v123, v98
	v_cvt_pk_bf16_f32 v176, v118, v119
	v_cvt_pk_bf16_f32 v177, v120, v121
	ds_read_b64_tr_b16 v[130:131], v219 offset:33792
	ds_read_b64_tr_b16 v[132:133], v219 offset:34304
	s_waitcnt lgkmcnt(11)
	v_mfma_f32_32x32x16_bf16 v[82:97], v[186:189], v[162:165], v[82:97]
	v_add_f32_e32 v98, v124, v98
	v_add_f32_e32 v98, v125, v98
	v_add_f32_e32 v98, v126, v98
	v_add_f32_e32 v98, v127, v98
	v_cvt_pk_bf16_f32 v166, v122, v123
	v_cvt_pk_bf16_f32 v167, v124, v125
	ds_read_b64_tr_b16 v[118:119], v219 offset:37888
	ds_read_b64_tr_b16 v[120:121], v219 offset:38400
	s_waitcnt lgkmcnt(12)
	v_mfma_f32_32x32x16_bf16 v[50:65], v[110:113], v[162:165], v[50:65]
	v_add_f32_e32 v98, v128, v98
	v_add_f32_e32 v98, v129, v98
	v_add_f32_e32 v98, v66, v98
	v_add_f32_e32 v98, v67, v98
	v_cvt_pk_bf16_f32 v168, v126, v127
	v_cvt_pk_bf16_f32 v169, v128, v129
	ds_read_b64_tr_b16 v[114:115], v219 offset:34816
	ds_read_b64_tr_b16 v[116:117], v219 offset:35328
	s_waitcnt lgkmcnt(13)
	v_mfma_f32_32x32x16_bf16 v[82:97], v[178:181], v[154:157], v[82:97]
	v_add_f32_e32 v98, v68, v98
	v_add_f32_e32 v98, v69, v98
	v_add_f32_e32 v98, v70, v98
	v_add_f32_e32 v98, v71, v98
	v_cvt_pk_bf16_f32 v158, v66, v67
	v_cvt_pk_bf16_f32 v159, v68, v69
	ds_read_b64_tr_b16 v[110:111], v219 offset:38912
	ds_read_b64_tr_b16 v[112:113], v219 offset:39424
	s_waitcnt lgkmcnt(14)
	v_mfma_f32_32x32x16_bf16 v[50:65], v[106:109], v[154:157], v[50:65]
	v_add_f32_e32 v66, v72, v98
	v_add_f32_e32 v66, v73, v66
	v_add_f32_e32 v66, v74, v66
	v_add_f32_e32 v66, v75, v66
	v_cvt_pk_bf16_f32 v160, v70, v71
	v_cvt_pk_bf16_f32 v161, v72, v73
	ds_read_b64_tr_b16 v[106:107], v219 offset:35840
	ds_read_b64_tr_b16 v[108:109], v219 offset:36352
	s_waitcnt lgkmcnt(14)
	v_mfma_f32_32x32x16_bf16 v[82:97], v[142:145], v[146:149], v[82:97]
	v_add_f32_e32 v66, v76, v66
	v_add_f32_e32 v66, v77, v66
	v_add_f32_e32 v66, v78, v66
	v_add_f32_e32 v66, v79, v66
	v_cvt_pk_bf16_f32 v150, v74, v75
	v_cvt_pk_bf16_f32 v151, v76, v77
	ds_read_b64_tr_b16 v[98:99], v219 offset:39936
	ds_read_b64_tr_b16 v[100:101], v219 offset:40448
	v_mfma_f32_32x32x16_bf16 v[50:65], v[102:105], v[146:149], v[50:65]
	v_add_f32_e32 v66, v80, v66
	v_add_f32_e32 v66, v81, v66
	v_add_f32_e32 v66, 0, v66
	v_cvt_pk_bf16_f32 v152, v78, v79
	v_cvt_pk_bf16_f32 v153, v80, v81
	s_nop 0
	s_nop 0
	v_max_f32_e32 v67, v82, v83
	s_nop 3
	v_max3_f32 v68, v84, v85, v51
	v_max3_f32 v67, v67, v50, v52
	v_max3_f32 v67, v67, v53, v86
	v_max3_f32 v68, v68, v88, v89
	v_max3_f32 v67, v67, v87, v54
	v_max3_f32 v68, v68, v56, v57
	v_max3_f32 v67, v67, v55, v90
	v_max3_f32 v68, v68, v92, v93
	v_max3_f32 v67, v67, v91, v58
	v_max3_f32 v68, v68, v60, v61
	v_max3_f32 v67, v67, v59, v94
	v_max3_f32 v68, v68, v96, v97
	v_max3_f32 v67, v67, v95, v62
	v_max3_f32 v68, v68, v64, v65
	v_add_f32_e32 v102, v190, v66
	v_max3_f32 v66, v67, v63, v68
	v_mov_b32_e32 v67, v66
	s_nop 1
	v_permlane32_swap_b32_e32 v66, v67
	s_nop 0
	s_nop 0
	v_max_f32_e32 v66, v66, v67
	v_cmp_lt_f32_e32 vcc, s48, v66
	s_cmp_lg_u64 vcc, 0
	s_cselect_b64 s[38:39], -1, 0
	s_cbranch_vccnz .LBB0_1321
